# P6 batch loads and stores use scalar base + 32-bit lane offset (row stepping on the SALU); ~96 VALU address instructions per 16-row batch removed
# speedup vs baseline: 1.0119x; 1.0059x over previous
; __device__ __forceinline__ void act_item(int item, u16* UP, const u16* HALO, const float* sconv, const float* wconv, const float* bconv, float* out, int lane) {
;     ...
;         for (int t = 0; t < 16; ++t) { const size_t row = (size_t)rb * 64 + tb + t; gw[t] = *(const unsigned*)(UP + row * FF2 + j0); vw[t] = *(const unsigned*)(UP + row * FF2 + FF + j0); }
.LBB0_775:
	s_add_u32 s98, s66, 0x4300000
	s_addc_u32 s99, s67, 0
	global_load_dword v47, v44, s[98:99]
	s_add_u32 s98, s98, 0x1600
	s_addc_u32 s99, s99, 0
	global_load_dword v46, v44, s[98:99]
	s_add_u32 s98, s98, 0x1600
	s_addc_u32 s99, s99, 0
	global_load_dword v58, v44, s[98:99]
	s_add_u32 s98, s98, 0x1600
	s_addc_u32 s99, s99, 0
	global_load_dword v59, v44, s[98:99]
	s_add_u32 s98, s98, 0x1600
	s_addc_u32 s99, s99, 0
	global_load_dword v56, v44, s[98:99]
	s_add_u32 s98, s98, 0x1600
	s_addc_u32 s99, s99, 0
	global_load_dword v57, v44, s[98:99]
	s_add_u32 s98, s98, 0x1600
	s_addc_u32 s99, s99, 0
	global_load_dword v87, v44, s[98:99]
	s_add_u32 s98, s98, 0x1600
	s_addc_u32 s99, s99, 0
	global_load_dword v88, v44, s[98:99]
	s_add_u32 s98, s98, 0x1600
	s_addc_u32 s99, s99, 0
	global_load_dword v86, v44, s[98:99]
	s_add_u32 s98, s98, 0x1600
	s_addc_u32 s99, s99, 0
	global_load_dword v85, v44, s[98:99]
	s_add_u32 s98, s98, 0x1600
	s_addc_u32 s99, s99, 0
	global_load_dword v83, v44, s[98:99]
	s_add_u32 s98, s98, 0x1600
	s_addc_u32 s99, s99, 0
	global_load_dword v84, v44, s[98:99]
	s_add_u32 s98, s98, 0x1600
	s_addc_u32 s99, s99, 0
	global_load_dword v81, v44, s[98:99]
	s_add_u32 s98, s98, 0x1600
	s_addc_u32 s99, s99, 0
	global_load_dword v82, v44, s[98:99]
	s_add_u32 s98, s98, 0x1600
	s_addc_u32 s99, s99, 0
	global_load_dword v79, v44, s[98:99]
	s_add_u32 s98, s98, 0x1600
	s_addc_u32 s99, s99, 0
	global_load_dword v80, v44, s[98:99]
	s_add_u32 s98, s98, 0x1600
	s_addc_u32 s99, s99, 0
	global_load_dword v78, v44, s[98:99]
	s_add_u32 s98, s98, 0x1600
	s_addc_u32 s99, s99, 0
	global_load_dword v77, v44, s[98:99]
	s_add_u32 s98, s98, 0x1600
	s_addc_u32 s99, s99, 0
	global_load_dword v75, v44, s[98:99]
	s_add_u32 s98, s98, 0x1600
	s_addc_u32 s99, s99, 0
	global_load_dword v76, v44, s[98:99]
	s_add_u32 s98, s98, 0x1600
	s_addc_u32 s99, s99, 0
	global_load_dword v73, v44, s[98:99]
	s_add_u32 s98, s98, 0x1600
	s_addc_u32 s99, s99, 0
	global_load_dword v74, v44, s[98:99]
	s_add_u32 s98, s98, 0x1600
	s_addc_u32 s99, s99, 0
	global_load_dword v71, v44, s[98:99]
	s_add_u32 s98, s98, 0x1600
	s_addc_u32 s99, s99, 0
	global_load_dword v72, v44, s[98:99]
	s_add_u32 s98, s98, 0x1600
	s_addc_u32 s99, s99, 0
	global_load_dword v70, v44, s[98:99]
	s_add_u32 s98, s98, 0x1600
	s_addc_u32 s99, s99, 0
	global_load_dword v69, v44, s[98:99]
	s_add_u32 s98, s98, 0x1600
	s_addc_u32 s99, s99, 0
	global_load_dword v66, v44, s[98:99]
	s_add_u32 s98, s98, 0x1600
	s_addc_u32 s99, s99, 0
	global_load_dword v67, v44, s[98:99]
	s_add_u32 s98, s98, 0x1600
	s_addc_u32 s99, s99, 0
	global_load_dword v64, v44, s[98:99]
	s_add_u32 s98, s98, 0x1600
	s_addc_u32 s99, s99, 0
	global_load_dword v65, v44, s[98:99]
	s_add_u32 s98, s98, 0x1600
	s_addc_u32 s99, s99, 0
	global_load_dword v1, v44, s[98:99]
	s_add_u32 s98, s98, 0x1600
	s_addc_u32 s99, s99, 0
	global_load_dword v68, v44, s[98:99]
	v_cndmask_b32_e64 v60, 0, 1, s[58:59]
	v_cmp_ne_u32_e64 s[6:7], 1, v60
	s_andn2_b64 vcc, exec, s[58:59]
	s_cbranch_vccnz .LBB0_777
	s_add_i32 s0, s81, s83
	s_addk_i32 s0, 0xc000
	s_ashr_i32 s0, s0, 2
	s_mul_hi_i32 s1, s0, 0xb000
	s_mul_i32 s0, s0, 0xb000
	s_add_u32 s0, s22, s0
	s_addc_u32 s1, s23, s1
	v_lshl_add_u64 v[48:49], v[2:3], 2, s[0:1]
	v_add_co_u32_e32 v50, vcc, 0x2000, v48
	s_nop 1
	v_addc_co_u32_e32 v51, vcc, 0, v49, vcc
	v_add_co_u32_e32 v52, vcc, 0x5000, v48
	s_nop 1
	v_addc_co_u32_e32 v53, vcc, 0, v49, vcc
	v_add_co_u32_e32 v54, vcc, 0x8000, v48
	s_nop 1
	v_addc_co_u32_e32 v55, vcc, 0, v49, vcc
	s_add_u32 s68, s0, 0xb000
	s_addc_u32 s69, s1, 0
	v_lshl_add_u64 v[100:101], v[2:3], 2, s[68:69]
	global_load_dwordx2 v[100:101], v[100:101], off
	s_add_u32 s68, s0, 0xdc00
	s_addc_u32 s69, s1, 0
	v_lshl_add_u64 v[102:103], v[2:3], 2, s[68:69]
	global_load_dwordx2 v[102:103], v[102:103], off
	s_add_u32 s68, s0, 0x10800
	s_addc_u32 s69, s1, 0
	v_lshl_add_u64 v[104:105], v[2:3], 2, s[68:69]
	global_load_dwordx2 v[104:105], v[104:105], off
	s_add_u32 s68, s0, 0x13400
	s_addc_u32 s69, s1, 0
	v_lshl_add_u64 v[106:107], v[2:3], 2, s[68:69]
	global_load_dwordx2 v[106:107], v[106:107], off
	s_add_u32 s68, s0, 0x16000
	s_addc_u32 s69, s1, 0
	v_lshl_add_u64 v[108:109], v[2:3], 2, s[68:69]
	global_load_dwordx2 v[108:109], v[108:109], off
	s_add_u32 s68, s0, 0x18c00
	s_addc_u32 s69, s1, 0
	v_lshl_add_u64 v[110:111], v[2:3], 2, s[68:69]
	global_load_dwordx2 v[110:111], v[110:111], off
	s_add_u32 s68, s0, 0x1b800
	s_addc_u32 s69, s1, 0
	v_lshl_add_u64 v[112:113], v[2:3], 2, s[68:69]
	global_load_dwordx2 v[112:113], v[112:113], off
	s_add_u32 s68, s0, 0x1e400
	s_addc_u32 s69, s1, 0
	v_lshl_add_u64 v[114:115], v[2:3], 2, s[68:69]
	global_load_dwordx2 v[114:115], v[114:115], off
	s_add_u32 s68, s0, 0x21000
	s_addc_u32 s69, s1, 0
	v_lshl_add_u64 v[116:117], v[2:3], 2, s[68:69]
	global_load_dwordx2 v[116:117], v[116:117], off
	s_add_u32 s68, s0, 0x23c00
	s_addc_u32 s69, s1, 0
	v_lshl_add_u64 v[118:119], v[2:3], 2, s[68:69]
	global_load_dwordx2 v[118:119], v[118:119], off
	s_add_u32 s68, s0, 0x26800
	s_addc_u32 s69, s1, 0
	v_lshl_add_u64 v[120:121], v[2:3], 2, s[68:69]
	global_load_dwordx2 v[120:121], v[120:121], off
	s_add_u32 s68, s0, 0x29400
	s_addc_u32 s69, s1, 0
	v_lshl_add_u64 v[122:123], v[2:3], 2, s[68:69]
	global_load_dwordx2 v[122:123], v[122:123], off
	global_load_dwordx2 v[48:49], v[48:49], off
	s_nop 0
	global_load_dwordx2 v[50:51], v[50:51], off offset:3072
	s_nop 0
	global_load_dwordx2 v[52:53], v[52:53], off offset:2048
	s_nop 0
	global_load_dwordx2 v[54:55], v[54:55], off offset:1024
; __device__ __forceinline__ float bf2f(unsigned b) { return __uint_as_float(b << 16); }
; __device__ __forceinline__ unsigned pk2(float lo, float hi) { unsigned r; asm("v_cvt_pk_bf16_f32 %0, %1, %2" : "=v"(r) : "v"(lo), "v"(hi)); return r; }
; __device__ __forceinline__ float gelu_t(float x) { return x * __builtin_amdgcn_rcpf(1.f + __expf(-1.5957691216057308f * (x + 0.044715f * x * x * x))); }
; __device__ __forceinline__ void act_item(int item, u16* UP, const u16* HALO, const float* sconv, const float* wconv, const float* bconv, float* out, int lane) {
;     ...
; #pragma unroll
;         for (int t = 0; t < 16; ++t) {
;             const int row = rb * 64 + tb + t;
;             if (sample && (t & 3) == 0) { const int ns = (row - TP) >> 2; const float* s0 = sconv + (size_t)ns * 2 * FF2;
;                 const f32x2 a = *(const f32x2*)(s0 + j0), b = *(const f32x2*)(s0 + FF + j0), c = *(const f32x2*)(s0 + FF2 + j0), dd = *(const f32x2*)(s0 + FF2 + FF + j0);
;                 g2[0] = a.x; g2[1] = a.y; v2[0] = b.x; v2[1] = b.y; g1[0] = c.x; g1[1] = c.y; v1[0] = dd.x; v1[1] = dd.y; }
;             const float g0[2] = {bf2f(gw[t] & 0xffffu), bf2f(gw[t] >> 16)}, v0[2] = {bf2f(vw[t] & 0xffffu), bf2f(vw[t] >> 16)};
;             float res[2];
; #pragma unroll
;             for (int p = 0; p < 2; ++p) { const float cgv = bg[p] + wgt[0][p] * g2[p] + wgt[1][p] * g1[p] + wgt[2][p] * g0[p];
;                 const float cvv = bv[p] + wvl[0][p] * v2[p] + wvl[1][p] * v1[p] + wvl[2][p] * v0[p]; res[p] = gelu_t(cgv) * cvv;
;                 g2[p] = g1[p]; g1[p] = g0[p]; v2[p] = v1[p]; v1[p] = v0[p]; }
;             *(unsigned*)(UP + (size_t)row * FF2 + j0) = pk2(res[0], res[1]);
.LBB0_777:
	s_waitcnt vmcnt(0)
	s_add_u32 s100, s64, 0x4300000
	s_addc_u32 s101, s65, 0
	v_lshlrev_b32_e32 v62, 16, v47
	v_and_b32_e32 v63, 0xffff0000, v47
	v_lshlrev_b32_e32 v89, 16, v46
	v_and_b32_e32 v90, 0xffff0000, v46
	v_pk_fma_f32 v[46:47], v[4:5], v[48:49], v[16:17]
	v_pk_fma_f32 v[48:49], v[6:7], v[50:51], v[18:19]
	v_pk_fma_f32 v[46:47], v[8:9], v[52:53], v[46:47]
	v_pk_fma_f32 v[48:49], v[10:11], v[54:55], v[48:49]
	v_fma_f32 v46, v12, v62, v46
	v_fmac_f32_e32 v47, v13, v63
	v_mul_f32_e32 v50, 0x3d372713, v46
	v_mul_f32_e32 v51, 0x3d372713, v47
	v_mul_f32_e32 v50, v46, v50
	v_mul_f32_e32 v51, v47, v51
	v_fma_f32 v50, v46, v50, v46
	v_fma_f32 v51, v47, v51, v47
	v_mul_f32_e32 v50, 0xbfcc422a, v50
	v_mul_f32_e32 v51, 0xbfcc422a, v51
	v_mul_f32_e32 v50, 0x3fb8aa3b, v50
	v_mul_f32_e32 v51, 0x3fb8aa3b, v51
	v_exp_f32_e32 v50, v50
	v_exp_f32_e32 v51, v51
	v_fma_f32 v48, v14, v89, v48
	v_fmac_f32_e32 v49, v15, v90
	v_add_f32_e32 v50, 1.0, v50
	v_add_f32_e32 v51, 1.0, v51
	v_rcp_f32_e32 v50, v50
	v_rcp_f32_e32 v51, v51
	v_pk_fma_f32 v[60:61], v[6:7], v[54:55], v[18:19]
	v_lshlrev_b32_e32 v54, 16, v57
	v_mul_f32_e32 v46, v46, v50
	v_mul_f32_e32 v47, v47, v51
	v_mul_f32_e32 v46, v48, v46
	v_mul_f32_e32 v47, v49, v47
	v_cvt_pk_bf16_f32 v50, v46, v47
	v_lshl_add_u64 v[46:47], s[64:65], 0, v[44:45]
	s_nop 0
	v_lshlrev_b32_e32 v51, 16, v58
	s_nop 0
	s_nop 0
	global_store_dword v44, v50, s[100:101]
	s_add_u32 s100, s100, 0x2c00
	s_addc_u32 s101, s101, 0
	v_lshlrev_b32_e32 v50, 16, v59
	v_and_b32_e32 v49, 0xffff0000, v58
	v_and_b32_e32 v48, 0xffff0000, v59
	v_pk_fma_f32 v[58:59], v[4:5], v[52:53], v[16:17]
	v_and_b32_e32 v52, 0xffff0000, v57
	v_fmac_f32_e32 v59, v9, v63
	v_fmac_f32_e32 v59, v13, v49
	v_fma_f32 v58, v8, v62, v58
	v_mul_f32_e32 v57, 0x3d372713, v59
	v_fmac_f32_e32 v58, v12, v51
	v_mul_f32_e32 v57, v59, v57
	v_lshlrev_b32_e32 v55, 16, v56
	v_and_b32_e32 v53, 0xffff0000, v56
	v_mul_f32_e32 v56, 0x3d372713, v58
	v_fma_f32 v57, v59, v57, v59
	v_mul_f32_e32 v56, v58, v56
	v_mul_f32_e32 v57, 0xbfcc422a, v57
	v_fma_f32 v56, v58, v56, v58
	v_mul_f32_e32 v57, 0x3fb8aa3b, v57
	v_mul_f32_e32 v56, 0xbfcc422a, v56
	v_exp_f32_e32 v57, v57
	v_mul_f32_e32 v56, 0x3fb8aa3b, v56
	v_exp_f32_e32 v56, v56
	v_fma_f32 v60, v10, v89, v60
	v_add_f32_e32 v57, 1.0, v57
	v_rcp_f32_e32 v57, v57
	v_add_f32_e32 v56, 1.0, v56
	v_rcp_f32_e32 v56, v56
	v_fmac_f32_e32 v60, v14, v50
	v_mul_f32_e32 v57, v59, v57
	v_fma_f32 v59, v4, v62, v16
	v_fmac_f32_e32 v59, v8, v51
	v_mul_f32_e32 v56, v58, v56
	v_fmac_f32_e32 v59, v12, v55
	v_mul_f32_e32 v56, v60, v56
	v_mul_f32_e32 v60, 0x3d372713, v59
	v_mul_f32_e32 v60, v59, v60
	v_fmac_f32_e32 v61, v11, v90
	v_fma_f32 v60, v59, v60, v59
	v_fmac_f32_e32 v61, v40, v48
	v_mul_f32_e32 v60, 0xbfcc422a, v60
	v_mul_f32_e32 v57, v61, v57
	v_cvt_pk_bf16_f32 v58, v56, v57
	s_nop 0
	v_mul_f32_e32 v60, 0x3fb8aa3b, v60
	s_nop 0
	s_nop 0
	v_exp_f32_e32 v60, v60
	global_store_dword v44, v58, s[100:101]
	s_add_u32 s100, s100, 0x2c00
	s_addc_u32 s101, s101, 0
	v_fma_f32 v58, v5, v63, v17
	v_fmac_f32_e32 v58, v9, v49
	v_fmac_f32_e32 v58, v13, v53
	v_add_f32_e32 v57, 1.0, v60
	v_mul_f32_e32 v60, 0x3d372713, v58
	v_mul_f32_e32 v60, v58, v60
	v_fma_f32 v60, v58, v60, v58
	v_mul_f32_e32 v60, 0xbfcc422a, v60
	v_rcp_f32_e32 v57, v57
	v_mul_f32_e32 v60, 0x3fb8aa3b, v60
	v_exp_f32_e32 v60, v60
	v_fma_f32 v56, v6, v89, v18
	v_fmac_f32_e32 v56, v10, v50
	v_fmac_f32_e32 v56, v14, v54
	v_mul_f32_e32 v57, v59, v57
	v_mul_f32_e32 v56, v56, v57
	v_add_f32_e32 v57, 1.0, v60
	v_rcp_f32_e32 v57, v57
	v_fma_f32 v59, v7, v90, v19
	v_fmac_f32_e32 v59, v42, v48
	v_fmac_f32_e32 v59, v40, v52
	v_mul_f32_e32 v57, v58, v57
	v_mul_f32_e32 v57, v59, v57
	v_cvt_pk_bf16_f32 v58, v56, v57
	s_nop 0
	v_mov_b32_e32 v62, v55
	s_nop 0
	s_nop 0
	global_store_dword v44, v58, s[100:101]
	s_add_u32 s100, s100, 0x2c00
	s_addc_u32 s101, s101, 0
	v_mov_b32_e32 v56, v54
	v_mov_b32_e32 v57, v52
	v_mov_b32_e32 v63, v53
	v_cndmask_b32_e64 v58, 0, 1, s[60:61]
	s_mov_b64 s[68:69], -1
	v_cmp_ne_u32_e64 s[0:1], 1, v58
	s_andn2_b64 vcc, exec, s[60:61]
	v_mov_b64_e32 v[58:59], v[62:63]
	v_mov_b64_e32 v[60:61], v[56:57]
	s_cbranch_vccnz .LBB0_779
	v_mov_b32_e32 v58, v55
	v_mov_b32_e32 v59, v53
	v_mov_b32_e32 v60, v54
	v_mov_b32_e32 v61, v52
	s_mov_b64 s[68:69], 0

; __device__ __forceinline__ unsigned pk2(float lo, float hi) { unsigned r; asm("v_cvt_pk_bf16_f32 %0, %1, %2" : "=v"(r) : "v"(lo), "v"(hi)); return r; }
; __device__ __forceinline__ float gelu_t(float x) { return x * __builtin_amdgcn_rcpf(1.f + __expf(-1.5957691216057308f * (x + 0.044715f * x * x * x))); }
; __device__ __forceinline__ void act_item(int item, u16* UP, const u16* HALO, const float* sconv, const float* wconv, const float* bconv, float* out, int lane) {
;     ...
;             for (int p = 0; p < 2; ++p) { const float cgv = bg[p] + wgt[0][p] * g2[p] + wgt[1][p] * g1[p] + wgt[2][p] * g0[p];
;                 const float cvv = bv[p] + wvl[0][p] * v2[p] + wvl[1][p] * v1[p] + wvl[2][p] * v0[p]; res[p] = gelu_t(cgv) * cvv;
;                 g2[p] = g1[p]; g1[p] = g0[p]; v2[p] = v1[p]; v1[p] = v0[p]; }
;             *(unsigned*)(UP + (size_t)row * FF2 + j0) = pk2(res[0], res[1]);
;             if (!sample) { const int tq = row & 2047; if (tq >= 2046) { float* o = out + O_CONVP + ((size_t)(row >> 11) * 2 + (tq - 2046)) * FF2;
;                     *(f32x2*)(o + j0) = (f32x2){g0[0], g0[1]}; *(f32x2*)(o + FF + j0) = (f32x2){v0[0], v0[1]}; } }
;             else if ((t & 3) >= 2) { const int ns = (row - TP) >> 2; float* o = out + O_CONVS + ((size_t)ns * 2 + ((t & 3) - 2)) * FF2;
;                     *(f32x2*)(o + j0) = (f32x2){g0[0], g0[1]}; *(f32x2*)(o + FF + j0) = (f32x2){v0[0], v0[1]}; }
.LBB0_781:
	v_pk_fma_f32 v[50:51], v[26:27], v[50:51], v[24:25]
	v_pk_fma_f32 v[48:49], v[34:35], v[48:49], v[32:33]
	v_lshlrev_b32_e32 v57, 16, v87
	v_lshlrev_b32_e32 v56, 16, v88
	v_and_b32_e32 v63, 0xffff0000, v87
	v_and_b32_e32 v62, 0xffff0000, v88
	v_pk_fma_f32 v[50:51], v[28:29], v[54:55], v[50:51]
	v_pk_fma_f32 v[48:49], v[36:37], v[52:53], v[48:49]
	v_pk_fma_f32 v[50:51], v[30:31], v[56:57], v[50:51]
	v_pk_fma_f32 v[48:49], v[38:39], v[62:63], v[48:49]
	v_mul_f32_e32 v54, 0x3d372713, v51
	v_mul_f32_e32 v52, 0x3d372713, v49
	v_mul_f32_e32 v54, v51, v54
	v_mul_f32_e32 v52, v49, v52
	v_fma_f32 v54, v51, v54, v51
	v_fma_f32 v52, v49, v52, v49
	v_mul_f32_e32 v54, 0xbfcc422a, v54
	v_mul_f32_e32 v52, 0xbfcc422a, v52
	v_mul_f32_e32 v54, 0x3fb8aa3b, v54
	v_mul_f32_e32 v52, 0x3fb8aa3b, v52
	v_exp_f32_e32 v54, v54
	v_exp_f32_e32 v52, v52
	v_add_f32_e32 v53, 1.0, v54
	v_add_f32_e32 v52, 1.0, v52
	v_rcp_f32_e32 v53, v53
	v_rcp_f32_e32 v52, v52
	v_mul_f32_e32 v51, v51, v53
	v_mul_f32_e32 v49, v49, v52
	v_mul_f32_e32 v50, v50, v51
	v_mul_f32_e32 v48, v48, v49
	v_cvt_pk_bf16_f32 v50, v50, v48
	s_nop 0
	v_mov_b32_e32 v52, v57
	s_nop 0
	s_nop 0
	v_mov_b32_e32 v53, v63
	v_mov_b32_e32 v57, v62
	s_and_b64 vcc, exec, s[6:7]
	global_store_dword v44, v50, s[100:101]
	s_add_u32 s100, s100, 0x2c00
	s_addc_u32 s101, s101, 0
	s_cbranch_vccnz .LBB0_783
	s_add_i32 s68, s81, s83
	s_addk_i32 s68, 0xc003
	s_ashr_i32 s68, s68, 2
	s_mul_hi_i32 s69, s68, 0xb000
	s_mul_i32 s68, s68, 0xb000
	s_add_u32 s68, s33, s68
	s_addc_u32 s69, s35, s69
	v_lshl_add_u64 v[48:49], v[2:3], 2, s[68:69]
	v_add_co_u32_e32 v50, vcc, 0x5000, v48
	s_nop 1
	v_addc_co_u32_e32 v51, vcc, 0, v49, vcc
	v_add_co_u32_e32 v48, vcc, 0x8000, v48
	global_store_dwordx2 v[50:51], v[52:53], off offset:2048
	s_nop 0
	v_addc_co_u32_e32 v49, vcc, 0, v49, vcc
	global_store_dwordx2 v[48:49], v[56:57], off offset:1024

; __device__ __forceinline__ float bf2f(unsigned b) { return __uint_as_float(b << 16); }
; __device__ __forceinline__ unsigned pk2(float lo, float hi) { unsigned r; asm("v_cvt_pk_bf16_f32 %0, %1, %2" : "=v"(r) : "v"(lo), "v"(hi)); return r; }
; __device__ __forceinline__ float gelu_t(float x) { return x * __builtin_amdgcn_rcpf(1.f + __expf(-1.5957691216057308f * (x + 0.044715f * x * x * x))); }
; __device__ __forceinline__ void act_item(int item, u16* UP, const u16* HALO, const float* sconv, const float* wconv, const float* bconv, float* out, int lane) {
;     ...
; #pragma unroll
;         for (int t = 0; t < 16; ++t) {
;             const int row = rb * 64 + tb + t;
;             if (sample && (t & 3) == 0) { const int ns = (row - TP) >> 2; const float* s0 = sconv + (size_t)ns * 2 * FF2;
;                 const f32x2 a = *(const f32x2*)(s0 + j0), b = *(const f32x2*)(s0 + FF + j0), c = *(const f32x2*)(s0 + FF2 + j0), dd = *(const f32x2*)(s0 + FF2 + FF + j0);
;                 g2[0] = a.x; g2[1] = a.y; v2[0] = b.x; v2[1] = b.y; g1[0] = c.x; g1[1] = c.y; v1[0] = dd.x; v1[1] = dd.y; }
;             const float g0[2] = {bf2f(gw[t] & 0xffffu), bf2f(gw[t] >> 16)}, v0[2] = {bf2f(vw[t] & 0xffffu), bf2f(vw[t] >> 16)};
;             float res[2];
; #pragma unroll
;             for (int p = 0; p < 2; ++p) { const float cgv = bg[p] + wgt[0][p] * g2[p] + wgt[1][p] * g1[p] + wgt[2][p] * g0[p];
;                 const float cvv = bv[p] + wvl[0][p] * v2[p] + wvl[1][p] * v1[p] + wvl[2][p] * v0[p]; res[p] = gelu_t(cgv) * cvv;
;                 g2[p] = g1[p]; g1[p] = g0[p]; v2[p] = v1[p]; v1[p] = v0[p]; }
;             *(unsigned*)(UP + (size_t)row * FF2 + j0) = pk2(res[0], res[1]);
.LBB0_785:
	v_pk_fma_f32 v[48:49], v[4:5], v[58:59], v[16:17]
	v_lshlrev_b32_e32 v62, 16, v86
	v_pk_fma_f32 v[48:49], v[8:9], v[52:53], v[48:49]
	v_and_b32_e32 v63, 0xffff0000, v86
	v_fma_f32 v48, v12, v62, v48
	v_mul_f32_e32 v54, 0x3d372713, v48
	v_fmac_f32_e32 v49, v13, v63
	v_mul_f32_e32 v54, v48, v54
	v_mul_f32_e32 v55, 0x3d372713, v49
	v_fma_f32 v54, v48, v54, v48
	v_mul_f32_e32 v55, v49, v55
	v_mul_f32_e32 v54, 0xbfcc422a, v54
	v_fma_f32 v55, v49, v55, v49
	v_mul_f32_e32 v54, 0x3fb8aa3b, v54
	v_mul_f32_e32 v55, 0xbfcc422a, v55
	v_exp_f32_e32 v54, v54
	v_mul_f32_e32 v55, 0x3fb8aa3b, v55
	v_exp_f32_e32 v55, v55
	v_pk_fma_f32 v[50:51], v[6:7], v[60:61], v[18:19]
	v_add_f32_e32 v54, 1.0, v54
	v_rcp_f32_e32 v54, v54
	v_add_f32_e32 v55, 1.0, v55
	v_rcp_f32_e32 v55, v55
	v_lshlrev_b32_e32 v86, 16, v85
	v_pk_fma_f32 v[50:51], v[10:11], v[56:57], v[50:51]
	v_and_b32_e32 v85, 0xffff0000, v85
	v_fma_f32 v50, v14, v86, v50
	v_mul_f32_e32 v48, v48, v54
	v_mul_f32_e32 v48, v50, v48
	v_fmac_f32_e32 v51, v15, v85
	v_mul_f32_e32 v49, v49, v55
	v_mul_f32_e32 v49, v51, v49
	v_cvt_pk_bf16_f32 v50, v48, v49
	s_nop 0
	v_pk_fma_f32 v[58:59], v[4:5], v[52:53], v[16:17]
	s_nop 0
	s_nop 0
	v_lshlrev_b32_e32 v51, 16, v83
	v_fma_f32 v58, v8, v62, v58
	global_store_dword v44, v50, s[100:101]
	s_add_u32 s100, s100, 0x2c00
	s_addc_u32 s101, s101, 0
	v_and_b32_e32 v49, 0xffff0000, v83
	v_fmac_f32_e32 v59, v9, v63
	v_fmac_f32_e32 v58, v12, v51
	v_mul_f32_e32 v60, 0x3d372713, v58
	v_fmac_f32_e32 v59, v13, v49
	v_mul_f32_e32 v60, v58, v60
	v_mul_f32_e32 v61, 0x3d372713, v59
	v_fma_f32 v60, v58, v60, v58
	v_mul_f32_e32 v61, v59, v61
	v_mul_f32_e32 v60, 0xbfcc422a, v60
	v_fma_f32 v61, v59, v61, v59
	v_mul_f32_e32 v60, 0x3fb8aa3b, v60
	v_mul_f32_e32 v61, 0xbfcc422a, v61
	v_exp_f32_e32 v60, v60
	v_mul_f32_e32 v61, 0x3fb8aa3b, v61
	v_exp_f32_e32 v61, v61
	v_pk_fma_f32 v[56:57], v[6:7], v[56:57], v[18:19]
	v_add_f32_e32 v60, 1.0, v60
	v_rcp_f32_e32 v60, v60
	v_add_f32_e32 v61, 1.0, v61
	v_rcp_f32_e32 v61, v61
	v_lshlrev_b32_e32 v50, 16, v84
	v_fma_f32 v56, v10, v86, v56
	v_fmac_f32_e32 v56, v14, v50
	v_mul_f32_e32 v58, v58, v60
	v_mul_f32_e32 v56, v56, v58
	v_mul_f32_e32 v58, v59, v61
	v_fma_f32 v59, v4, v62, v16
	v_lshlrev_b32_e32 v55, 16, v81
	v_fmac_f32_e32 v59, v8, v51
	v_fmac_f32_e32 v59, v12, v55
	v_mul_f32_e32 v60, 0x3d372713, v59
	v_mul_f32_e32 v60, v59, v60
	v_and_b32_e32 v48, 0xffff0000, v84
	v_fmac_f32_e32 v57, v11, v85
	v_fma_f32 v60, v59, v60, v59
	v_fmac_f32_e32 v57, v40, v48
	v_mul_f32_e32 v60, 0xbfcc422a, v60
	v_mul_f32_e32 v57, v57, v58
	v_cvt_pk_bf16_f32 v58, v56, v57
	s_nop 0
	v_mul_f32_e32 v60, 0x3fb8aa3b, v60
	s_nop 0
	s_nop 0
	v_exp_f32_e32 v60, v60
	global_store_dword v44, v58, s[100:101]
	s_add_u32 s100, s100, 0x2c00
	s_addc_u32 s101, s101, 0
	v_fma_f32 v58, v5, v63, v17
	v_and_b32_e32 v53, 0xffff0000, v81
	v_fmac_f32_e32 v58, v9, v49
	v_fmac_f32_e32 v58, v13, v53
	v_add_f32_e32 v57, 1.0, v60
	v_mul_f32_e32 v60, 0x3d372713, v58
	v_mul_f32_e32 v60, v58, v60
	v_fma_f32 v60, v58, v60, v58
	v_mul_f32_e32 v60, 0xbfcc422a, v60
	v_rcp_f32_e32 v57, v57
	v_mul_f32_e32 v60, 0x3fb8aa3b, v60
	v_exp_f32_e32 v60, v60
	v_fma_f32 v56, v6, v86, v18
	v_lshlrev_b32_e32 v54, 16, v82
	v_fmac_f32_e32 v56, v10, v50
	v_fmac_f32_e32 v56, v14, v54
	v_mul_f32_e32 v57, v59, v57
	v_mul_f32_e32 v56, v56, v57
	v_add_f32_e32 v57, 1.0, v60
	v_rcp_f32_e32 v57, v57
	v_fma_f32 v59, v7, v85, v19
	v_and_b32_e32 v52, 0xffff0000, v82
	v_fmac_f32_e32 v59, v42, v48
	v_fmac_f32_e32 v59, v40, v52
	v_mul_f32_e32 v57, v58, v57
	v_mul_f32_e32 v57, v59, v57
	v_cvt_pk_bf16_f32 v58, v56, v57
	s_nop 0
	v_mov_b32_e32 v59, v52
	s_nop 0
	s_nop 0
	global_store_dword v44, v58, s[100:101]
	s_add_u32 s100, s100, 0x2c00
	s_addc_u32 s101, s101, 0
	v_mov_b32_e32 v58, v54
	v_mov_b32_e32 v62, v55
	v_mov_b32_e32 v63, v53
	s_mov_b64 s[68:69], -1
	s_and_b64 vcc, exec, s[0:1]
	v_mov_b64_e32 v[56:57], v[62:63]
	v_mov_b64_e32 v[60:61], v[58:59]
	s_cbranch_vccnz .LBB0_787
	v_mov_b32_e32 v56, v55
	v_mov_b32_e32 v57, v53
	v_mov_b32_e32 v60, v54
	v_mov_b32_e32 v61, v52
	s_mov_b64 s[68:69], 0

; __device__ __forceinline__ unsigned pk2(float lo, float hi) { unsigned r; asm("v_cvt_pk_bf16_f32 %0, %1, %2" : "=v"(r) : "v"(lo), "v"(hi)); return r; }
; __device__ __forceinline__ float gelu_t(float x) { return x * __builtin_amdgcn_rcpf(1.f + __expf(-1.5957691216057308f * (x + 0.044715f * x * x * x))); }
; __device__ __forceinline__ void act_item(int item, u16* UP, const u16* HALO, const float* sconv, const float* wconv, const float* bconv, float* out, int lane) {
;     ...
;             for (int p = 0; p < 2; ++p) { const float cgv = bg[p] + wgt[0][p] * g2[p] + wgt[1][p] * g1[p] + wgt[2][p] * g0[p];
;                 const float cvv = bv[p] + wvl[0][p] * v2[p] + wvl[1][p] * v1[p] + wvl[2][p] * v0[p]; res[p] = gelu_t(cgv) * cvv;
;                 g2[p] = g1[p]; g1[p] = g0[p]; v2[p] = v1[p]; v1[p] = v0[p]; }
;             *(unsigned*)(UP + (size_t)row * FF2 + j0) = pk2(res[0], res[1]);
;             if (!sample) { const int tq = row & 2047; if (tq >= 2046) { float* o = out + O_CONVP + ((size_t)(row >> 11) * 2 + (tq - 2046)) * FF2;
;                     *(f32x2*)(o + j0) = (f32x2){g0[0], g0[1]}; *(f32x2*)(o + FF + j0) = (f32x2){v0[0], v0[1]}; } }
;             else if ((t & 3) >= 2) { const int ns = (row - TP) >> 2; float* o = out + O_CONVS + ((size_t)ns * 2 + ((t & 3) - 2)) * FF2;
;                     *(f32x2*)(o + j0) = (f32x2){g0[0], g0[1]}; *(f32x2*)(o + FF + j0) = (f32x2){v0[0], v0[1]}; }
.LBB0_789:
	v_pk_fma_f32 v[48:49], v[34:35], v[48:49], v[32:33]
	v_and_b32_e32 v63, 0xffff0000, v79
	v_and_b32_e32 v62, 0xffff0000, v80
	v_pk_fma_f32 v[50:51], v[26:27], v[50:51], v[24:25]
	v_pk_fma_f32 v[48:49], v[36:37], v[52:53], v[48:49]
	v_lshlrev_b32_e32 v59, 16, v79
	v_lshlrev_b32_e32 v58, 16, v80
	v_pk_fma_f32 v[50:51], v[28:29], v[54:55], v[50:51]
	v_pk_fma_f32 v[48:49], v[38:39], v[62:63], v[48:49]
	v_pk_fma_f32 v[50:51], v[30:31], v[58:59], v[50:51]
	v_mul_f32_e32 v52, 0x3d372713, v49
	v_mul_f32_e32 v54, 0x3d372713, v51
	v_mul_f32_e32 v52, v49, v52
	v_mul_f32_e32 v54, v51, v54
	v_fma_f32 v52, v49, v52, v49
	v_fma_f32 v54, v51, v54, v51
	v_mul_f32_e32 v52, 0xbfcc422a, v52
	v_mul_f32_e32 v54, 0xbfcc422a, v54
	v_mul_f32_e32 v52, 0x3fb8aa3b, v52
	v_mul_f32_e32 v54, 0x3fb8aa3b, v54
	v_exp_f32_e32 v52, v52
	v_exp_f32_e32 v54, v54
	v_add_f32_e32 v52, 1.0, v52
	v_add_f32_e32 v53, 1.0, v54
	v_rcp_f32_e32 v52, v52
	v_rcp_f32_e32 v53, v53
	v_mul_f32_e32 v49, v49, v52
	v_mul_f32_e32 v51, v51, v53
	v_mul_f32_e32 v48, v48, v49
	v_mul_f32_e32 v53, v50, v51
	v_cvt_pk_bf16_f32 v52, v53, v48
	s_nop 0
	v_mov_b32_e32 v50, v59
	s_nop 0
	s_nop 0
	v_mov_b32_e32 v51, v63
	v_mov_b32_e32 v59, v62
	s_and_b64 vcc, exec, s[6:7]
	global_store_dword v44, v52, s[100:101]
	s_add_u32 s100, s100, 0x2c00
	s_addc_u32 s101, s101, 0
	s_cbranch_vccnz .LBB0_791
	s_add_i32 s68, s81, s83
	s_addk_i32 s68, 0xc007
	s_ashr_i32 s68, s68, 2
	s_mul_hi_i32 s69, s68, 0xb000
	s_mul_i32 s68, s68, 0xb000
	s_add_u32 s68, s33, s68
	s_addc_u32 s69, s35, s69
	v_lshl_add_u64 v[48:49], v[2:3], 2, s[68:69]
	v_add_co_u32_e32 v52, vcc, 0x5000, v48
	s_nop 1
	v_addc_co_u32_e32 v53, vcc, 0, v49, vcc
	v_add_co_u32_e32 v48, vcc, 0x8000, v48
	global_store_dwordx2 v[52:53], v[50:51], off offset:2048
	s_nop 0
	v_addc_co_u32_e32 v49, vcc, 0, v49, vcc
	global_store_dwordx2 v[48:49], v[58:59], off offset:1024

; __device__ __forceinline__ float bf2f(unsigned b) { return __uint_as_float(b << 16); }
; __device__ __forceinline__ unsigned pk2(float lo, float hi) { unsigned r; asm("v_cvt_pk_bf16_f32 %0, %1, %2" : "=v"(r) : "v"(lo), "v"(hi)); return r; }
; __device__ __forceinline__ float gelu_t(float x) { return x * __builtin_amdgcn_rcpf(1.f + __expf(-1.5957691216057308f * (x + 0.044715f * x * x * x))); }
; __device__ __forceinline__ void act_item(int item, u16* UP, const u16* HALO, const float* sconv, const float* wconv, const float* bconv, float* out, int lane) {
;     ...
; #pragma unroll
;         for (int t = 0; t < 16; ++t) {
;             const int row = rb * 64 + tb + t;
;             if (sample && (t & 3) == 0) { const int ns = (row - TP) >> 2; const float* s0 = sconv + (size_t)ns * 2 * FF2;
;                 const f32x2 a = *(const f32x2*)(s0 + j0), b = *(const f32x2*)(s0 + FF + j0), c = *(const f32x2*)(s0 + FF2 + j0), dd = *(const f32x2*)(s0 + FF2 + FF + j0);
;                 g2[0] = a.x; g2[1] = a.y; v2[0] = b.x; v2[1] = b.y; g1[0] = c.x; g1[1] = c.y; v1[0] = dd.x; v1[1] = dd.y; }
;             const float g0[2] = {bf2f(gw[t] & 0xffffu), bf2f(gw[t] >> 16)}, v0[2] = {bf2f(vw[t] & 0xffffu), bf2f(vw[t] >> 16)};
;             float res[2];
; #pragma unroll
;             for (int p = 0; p < 2; ++p) { const float cgv = bg[p] + wgt[0][p] * g2[p] + wgt[1][p] * g1[p] + wgt[2][p] * g0[p];
;                 const float cvv = bv[p] + wvl[0][p] * v2[p] + wvl[1][p] * v1[p] + wvl[2][p] * v0[p]; res[p] = gelu_t(cgv) * cvv;
;                 g2[p] = g1[p]; g1[p] = g0[p]; v2[p] = v1[p]; v1[p] = v0[p]; }
;             *(unsigned*)(UP + (size_t)row * FF2 + j0) = pk2(res[0], res[1]);
.LBB0_793:
	v_pk_fma_f32 v[48:49], v[4:5], v[56:57], v[16:17]
	v_lshlrev_b32_e32 v54, 16, v78
	v_pk_fma_f32 v[48:49], v[8:9], v[50:51], v[48:49]
	v_and_b32_e32 v55, 0xffff0000, v78
	v_fma_f32 v48, v12, v54, v48
	v_mul_f32_e32 v56, 0x3d372713, v48
	v_fmac_f32_e32 v49, v13, v55
	v_mul_f32_e32 v56, v48, v56
	v_mul_f32_e32 v57, 0x3d372713, v49
	v_fma_f32 v56, v48, v56, v48
	v_mul_f32_e32 v57, v49, v57
	v_mul_f32_e32 v56, 0xbfcc422a, v56
	v_fma_f32 v57, v49, v57, v49
	v_mul_f32_e32 v56, 0x3fb8aa3b, v56
	v_mul_f32_e32 v57, 0xbfcc422a, v57
	v_exp_f32_e32 v56, v56
	v_mul_f32_e32 v57, 0x3fb8aa3b, v57
	v_exp_f32_e32 v57, v57
	v_pk_fma_f32 v[52:53], v[6:7], v[60:61], v[18:19]
	v_add_f32_e32 v56, 1.0, v56
	v_rcp_f32_e32 v56, v56
	v_add_f32_e32 v57, 1.0, v57
	v_rcp_f32_e32 v57, v57
	v_lshlrev_b32_e32 v62, 16, v77
	v_pk_fma_f32 v[52:53], v[10:11], v[58:59], v[52:53]
	v_and_b32_e32 v63, 0xffff0000, v77
	v_fma_f32 v52, v14, v62, v52
	v_mul_f32_e32 v48, v48, v56
	v_mul_f32_e32 v48, v52, v48
	v_fmac_f32_e32 v53, v15, v63
	v_mul_f32_e32 v49, v49, v57
	v_mul_f32_e32 v49, v53, v49
	v_cvt_pk_bf16_f32 v52, v48, v49
	s_nop 0
	v_pk_fma_f32 v[50:51], v[4:5], v[50:51], v[16:17]
	s_nop 0
	s_nop 0
	global_store_dword v44, v52, s[100:101]
	s_add_u32 s100, s100, 0x2c00
	s_addc_u32 s101, s101, 0
	v_and_b32_e32 v49, 0xffff0000, v75
	v_fmac_f32_e32 v51, v9, v55
	v_fmac_f32_e32 v51, v13, v49
	v_pk_fma_f32 v[52:53], v[6:7], v[58:59], v[18:19]
	v_lshlrev_b32_e32 v60, 16, v74
	v_and_b32_e32 v58, 0xffff0000, v74
	v_mul_f32_e32 v74, 0x3d372713, v51
	v_mul_f32_e32 v74, v51, v74
	v_fma_f32 v74, v51, v74, v51
	v_mul_f32_e32 v74, 0xbfcc422a, v74
	v_lshlrev_b32_e32 v57, 16, v75
	v_fma_f32 v50, v8, v54, v50
	v_mul_f32_e32 v74, 0x3fb8aa3b, v74
	v_fmac_f32_e32 v50, v12, v57
	v_exp_f32_e32 v74, v74
	v_lshlrev_b32_e32 v61, 16, v73
	v_and_b32_e32 v59, 0xffff0000, v73
	v_mul_f32_e32 v73, 0x3d372713, v50
	v_mul_f32_e32 v73, v50, v73
	v_fma_f32 v73, v50, v73, v50
	v_mul_f32_e32 v73, 0xbfcc422a, v73
	v_add_f32_e32 v74, 1.0, v74
	v_mul_f32_e32 v73, 0x3fb8aa3b, v73
	v_rcp_f32_e32 v74, v74
	v_exp_f32_e32 v73, v73
	v_and_b32_e32 v48, 0xffff0000, v76
	v_fmac_f32_e32 v53, v11, v63
	v_fmac_f32_e32 v53, v40, v48
	v_mul_f32_e32 v51, v51, v74
	v_add_f32_e32 v73, 1.0, v73
	v_mul_f32_e32 v51, v53, v51
	v_fma_f32 v53, v4, v54, v16
	v_rcp_f32_e32 v73, v73
	v_fmac_f32_e32 v53, v8, v57
	v_fmac_f32_e32 v53, v12, v61
	v_mul_f32_e32 v54, 0x3d372713, v53
	v_lshlrev_b32_e32 v56, 16, v76
	v_fma_f32 v52, v10, v62, v52
	v_mul_f32_e32 v54, v53, v54
	v_fmac_f32_e32 v52, v14, v56
	v_mul_f32_e32 v50, v50, v73
	v_fma_f32 v54, v53, v54, v53
	v_mul_f32_e32 v50, v52, v50
	v_mul_f32_e32 v54, 0xbfcc422a, v54
	v_cvt_pk_bf16_f32 v52, v50, v51
	s_nop 0
	v_mul_f32_e32 v54, 0x3fb8aa3b, v54
	s_nop 0
	s_nop 0
	v_exp_f32_e32 v54, v54
	global_store_dword v44, v52, s[100:101]
	s_add_u32 s100, s100, 0x2c00
	s_addc_u32 s101, s101, 0
	v_fma_f32 v52, v5, v55, v17
	v_fmac_f32_e32 v52, v9, v49
	v_fmac_f32_e32 v52, v13, v59
	v_add_f32_e32 v51, 1.0, v54
	v_mul_f32_e32 v54, 0x3d372713, v52
	v_mul_f32_e32 v54, v52, v54
	v_fma_f32 v54, v52, v54, v52
	v_mul_f32_e32 v54, 0xbfcc422a, v54
	v_rcp_f32_e32 v51, v51
	v_mul_f32_e32 v54, 0x3fb8aa3b, v54
	v_exp_f32_e32 v54, v54
	v_fma_f32 v50, v6, v62, v18
	v_fmac_f32_e32 v50, v10, v56
	v_fmac_f32_e32 v50, v14, v60
	v_mul_f32_e32 v51, v53, v51
	v_mul_f32_e32 v50, v50, v51
	v_add_f32_e32 v51, 1.0, v54
	v_rcp_f32_e32 v51, v51
	v_fma_f32 v53, v7, v63, v19
	v_fmac_f32_e32 v53, v42, v48
	v_fmac_f32_e32 v53, v40, v58
	v_mul_f32_e32 v51, v52, v51
	v_mul_f32_e32 v51, v53, v51
	v_cvt_pk_bf16_f32 v52, v50, v51
	s_nop 0
	v_mov_b32_e32 v62, v61
	s_nop 0
	s_nop 0
	global_store_dword v44, v52, s[100:101]
	s_add_u32 s100, s100, 0x2c00
	s_addc_u32 s101, s101, 0
	v_mov_b32_e32 v50, v60
	v_mov_b32_e32 v51, v58
	v_mov_b32_e32 v63, v59
	s_mov_b64 s[68:69], -1
	s_and_b64 vcc, exec, s[0:1]
	v_mov_b64_e32 v[52:53], v[62:63]
	v_mov_b64_e32 v[54:55], v[50:51]
	s_cbranch_vccnz .LBB0_795
	v_mov_b32_e32 v52, v61
	v_mov_b32_e32 v53, v59
	v_mov_b32_e32 v54, v60
	v_mov_b32_e32 v55, v58
	s_mov_b64 s[68:69], 0

; __device__ __forceinline__ unsigned pk2(float lo, float hi) { unsigned r; asm("v_cvt_pk_bf16_f32 %0, %1, %2" : "=v"(r) : "v"(lo), "v"(hi)); return r; }
; __device__ __forceinline__ float gelu_t(float x) { return x * __builtin_amdgcn_rcpf(1.f + __expf(-1.5957691216057308f * (x + 0.044715f * x * x * x))); }
; __device__ __forceinline__ void act_item(int item, u16* UP, const u16* HALO, const float* sconv, const float* wconv, const float* bconv, float* out, int lane) {
;     ...
;             for (int p = 0; p < 2; ++p) { const float cgv = bg[p] + wgt[0][p] * g2[p] + wgt[1][p] * g1[p] + wgt[2][p] * g0[p];
;                 const float cvv = bv[p] + wvl[0][p] * v2[p] + wvl[1][p] * v1[p] + wvl[2][p] * v0[p]; res[p] = gelu_t(cgv) * cvv;
;                 g2[p] = g1[p]; g1[p] = g0[p]; v2[p] = v1[p]; v1[p] = v0[p]; }
;             *(unsigned*)(UP + (size_t)row * FF2 + j0) = pk2(res[0], res[1]);
;             if (!sample) { const int tq = row & 2047; if (tq >= 2046) { float* o = out + O_CONVP + ((size_t)(row >> 11) * 2 + (tq - 2046)) * FF2;
;                     *(f32x2*)(o + j0) = (f32x2){g0[0], g0[1]}; *(f32x2*)(o + FF + j0) = (f32x2){v0[0], v0[1]}; } }
;             else if ((t & 3) >= 2) { const int ns = (row - TP) >> 2; float* o = out + O_CONVS + ((size_t)ns * 2 + ((t & 3) - 2)) * FF2;
;                     *(f32x2*)(o + j0) = (f32x2){g0[0], g0[1]}; *(f32x2*)(o + FF + j0) = (f32x2){v0[0], v0[1]}; }
.LBB0_797:
	v_pk_fma_f32 v[56:57], v[26:27], v[56:57], v[24:25]
	v_lshlrev_b32_e32 v51, 16, v71
	v_lshlrev_b32_e32 v50, 16, v72
	v_pk_fma_f32 v[56:57], v[28:29], v[60:61], v[56:57]
	v_pk_fma_f32 v[48:49], v[34:35], v[48:49], v[32:33]
	v_and_b32_e32 v63, 0xffff0000, v71
	v_and_b32_e32 v62, 0xffff0000, v72
	v_pk_fma_f32 v[56:57], v[30:31], v[50:51], v[56:57]
	v_pk_fma_f32 v[48:49], v[36:37], v[58:59], v[48:49]
	v_mul_f32_e32 v60, 0x3d372713, v57
	v_pk_fma_f32 v[48:49], v[38:39], v[62:63], v[48:49]
	v_mul_f32_e32 v60, v57, v60
	v_mul_f32_e32 v58, 0x3d372713, v49
	v_fma_f32 v60, v57, v60, v57
	v_mul_f32_e32 v58, v49, v58
	v_mul_f32_e32 v60, 0xbfcc422a, v60
	v_fma_f32 v58, v49, v58, v49
	v_mul_f32_e32 v60, 0x3fb8aa3b, v60
	v_mul_f32_e32 v58, 0xbfcc422a, v58
	v_exp_f32_e32 v60, v60
	v_mul_f32_e32 v58, 0x3fb8aa3b, v58
	v_exp_f32_e32 v58, v58
	v_add_f32_e32 v59, 1.0, v60
	v_rcp_f32_e32 v59, v59
	v_add_f32_e32 v58, 1.0, v58
	v_rcp_f32_e32 v58, v58
	v_mul_f32_e32 v57, v57, v59
	v_mul_f32_e32 v56, v56, v57
	v_mul_f32_e32 v49, v49, v58
	v_mul_f32_e32 v57, v48, v49
	v_cvt_pk_bf16_f32 v58, v56, v57
	s_nop 0
	v_mov_b32_e32 v48, v51
	s_nop 0
	s_nop 0
	v_mov_b32_e32 v49, v63
	v_mov_b32_e32 v51, v62
	s_and_b64 vcc, exec, s[6:7]
	global_store_dword v44, v58, s[100:101]
	s_add_u32 s100, s100, 0x2c00
	s_addc_u32 s101, s101, 0
	s_cbranch_vccnz .LBB0_812
	s_add_i32 s6, s81, s83
	s_addk_i32 s6, 0xc00b
	s_ashr_i32 s6, s6, 2
	s_mul_hi_i32 s7, s6, 0xb000
	s_mul_i32 s6, s6, 0xb000
	s_add_u32 s6, s33, s6
	s_addc_u32 s7, s35, s7
	v_lshl_add_u64 v[56:57], v[2:3], 2, s[6:7]
	v_add_co_u32_e32 v58, vcc, 0x5000, v56
	s_nop 1
	v_addc_co_u32_e32 v59, vcc, 0, v57, vcc
	v_add_co_u32_e32 v56, vcc, 0x8000, v56
	global_store_dwordx2 v[58:59], v[48:49], off offset:2048
	s_nop 0
	v_addc_co_u32_e32 v57, vcc, 0, v57, vcc
	global_store_dwordx2 v[56:57], v[50:51], off offset:1024
	s_and_b64 vcc, exec, s[0:1]
	s_mov_b64 s[6:7], -1
	s_cbranch_vccz .LBB0_813

; __device__ __forceinline__ float bf2f(unsigned b) { return __uint_as_float(b << 16); }
; __device__ __forceinline__ unsigned pk2(float lo, float hi) { unsigned r; asm("v_cvt_pk_bf16_f32 %0, %1, %2" : "=v"(r) : "v"(lo), "v"(hi)); return r; }
; __device__ __forceinline__ float gelu_t(float x) { return x * __builtin_amdgcn_rcpf(1.f + __expf(-1.5957691216057308f * (x + 0.044715f * x * x * x))); }
; __device__ __forceinline__ void act_item(int item, u16* UP, const u16* HALO, const float* sconv, const float* wconv, const float* bconv, float* out, int lane) {
;     ...
; #pragma unroll
;         for (int t = 0; t < 16; ++t) {
;             const int row = rb * 64 + tb + t;
;             if (sample && (t & 3) == 0) { const int ns = (row - TP) >> 2; const float* s0 = sconv + (size_t)ns * 2 * FF2;
;                 const f32x2 a = *(const f32x2*)(s0 + j0), b = *(const f32x2*)(s0 + FF + j0), c = *(const f32x2*)(s0 + FF2 + j0), dd = *(const f32x2*)(s0 + FF2 + FF + j0);
;                 g2[0] = a.x; g2[1] = a.y; v2[0] = b.x; v2[1] = b.y; g1[0] = c.x; g1[1] = c.y; v1[0] = dd.x; v1[1] = dd.y; }
;             const float g0[2] = {bf2f(gw[t] & 0xffffu), bf2f(gw[t] >> 16)}, v0[2] = {bf2f(vw[t] & 0xffffu), bf2f(vw[t] >> 16)};
;             float res[2];
; #pragma unroll
;             for (int p = 0; p < 2; ++p) { const float cgv = bg[p] + wgt[0][p] * g2[p] + wgt[1][p] * g1[p] + wgt[2][p] * g0[p];
;                 const float cvv = bv[p] + wvl[0][p] * v2[p] + wvl[1][p] * v1[p] + wvl[2][p] * v0[p]; res[p] = gelu_t(cgv) * cvv;
;                 g2[p] = g1[p]; g1[p] = g0[p]; v2[p] = v1[p]; v1[p] = v0[p]; }
;             *(unsigned*)(UP + (size_t)row * FF2 + j0) = pk2(res[0], res[1]);
;             if (!sample) { const int tq = row & 2047; if (tq >= 2046) { float* o = out + O_CONVP + ((size_t)(row >> 11) * 2 + (tq - 2046)) * FF2;
;                     *(f32x2*)(o + j0) = (f32x2){g0[0], g0[1]}; *(f32x2*)(o + FF + j0) = (f32x2){v0[0], v0[1]}; } }
.LBB0_801:
	v_pk_fma_f32 v[52:53], v[4:5], v[52:53], v[16:17]
	v_lshlrev_b32_e32 v71, 16, v70
	v_pk_fma_f32 v[52:53], v[8:9], v[48:49], v[52:53]
	v_and_b32_e32 v70, 0xffff0000, v70
	v_fma_f32 v52, v12, v71, v52
	v_mul_f32_e32 v56, 0x3d372713, v52
	v_fmac_f32_e32 v53, v13, v70
	v_mul_f32_e32 v56, v52, v56
	v_mul_f32_e32 v57, 0x3d372713, v53
	v_fma_f32 v56, v52, v56, v52
	v_mul_f32_e32 v57, v53, v57
	v_mul_f32_e32 v56, 0xbfcc422a, v56
	v_fma_f32 v57, v53, v57, v53
	v_mul_f32_e32 v56, 0x3fb8aa3b, v56
	v_mul_f32_e32 v57, 0xbfcc422a, v57
	v_exp_f32_e32 v56, v56
	v_mul_f32_e32 v57, 0x3fb8aa3b, v57
	v_exp_f32_e32 v57, v57
	v_pk_fma_f32 v[54:55], v[6:7], v[54:55], v[18:19]
	v_add_f32_e32 v56, 1.0, v56
	v_rcp_f32_e32 v56, v56
	v_add_f32_e32 v57, 1.0, v57
	v_rcp_f32_e32 v57, v57
	v_lshlrev_b32_e32 v72, 16, v69
	v_pk_fma_f32 v[54:55], v[10:11], v[50:51], v[54:55]
	v_and_b32_e32 v69, 0xffff0000, v69
	v_fma_f32 v54, v14, v72, v54
	v_mul_f32_e32 v52, v52, v56
	v_mul_f32_e32 v52, v54, v52
	v_fmac_f32_e32 v55, v15, v69
	v_mul_f32_e32 v53, v53, v57
	v_pk_fma_f32 v[48:49], v[4:5], v[48:49], v[16:17]
	v_mul_f32_e32 v53, v55, v53
	v_cvt_pk_bf16_f32 v54, v52, v53
	s_nop 0
	v_and_b32_e32 v57, 0xffff0000, v66
	v_fmac_f32_e32 v49, v9, v70
	s_nop 0
	v_fmac_f32_e32 v49, v13, v57
	global_store_dword v44, v54, s[100:101]
	s_add_u32 s100, s100, 0x2c00
	s_addc_u32 s101, s101, 0
	v_mul_f32_e32 v53, 0x3d372713, v49
	v_mul_f32_e32 v53, v49, v53
	v_lshlrev_b32_e32 v59, 16, v66
	v_fma_f32 v48, v8, v71, v48
	v_fma_f32 v53, v49, v53, v49
	v_fmac_f32_e32 v48, v12, v59
	v_mul_f32_e32 v53, 0xbfcc422a, v53
	v_mul_f32_e32 v52, 0x3d372713, v48
	v_mul_f32_e32 v53, 0x3fb8aa3b, v53
	v_mul_f32_e32 v52, v48, v52
	v_exp_f32_e32 v53, v53
	v_fma_f32 v52, v48, v52, v48
	v_mul_f32_e32 v52, 0xbfcc422a, v52
	v_mul_f32_e32 v52, 0x3fb8aa3b, v52
	v_exp_f32_e32 v52, v52
	v_add_f32_e32 v53, 1.0, v53
	v_rcp_f32_e32 v53, v53
	v_pk_fma_f32 v[50:51], v[6:7], v[50:51], v[18:19]
	v_and_b32_e32 v56, 0xffff0000, v67
	v_fmac_f32_e32 v51, v11, v69
	v_add_f32_e32 v52, 1.0, v52
	v_rcp_f32_e32 v52, v52
	v_fmac_f32_e32 v51, v40, v56
	v_mul_f32_e32 v49, v49, v53
	v_mul_f32_e32 v49, v51, v49
	v_fma_f32 v51, v4, v71, v16
	v_lshlrev_b32_e32 v63, 16, v64
	v_fmac_f32_e32 v51, v8, v59
	v_fmac_f32_e32 v51, v12, v63
	v_mul_f32_e32 v48, v48, v52
	v_mul_f32_e32 v52, 0x3d372713, v51
	v_lshlrev_b32_e32 v58, 16, v67
	v_fma_f32 v50, v10, v72, v50
	v_mul_f32_e32 v52, v51, v52
	v_fmac_f32_e32 v50, v14, v58
	v_fma_f32 v52, v51, v52, v51
	v_mul_f32_e32 v48, v50, v48
	v_mul_f32_e32 v52, 0xbfcc422a, v52
	v_cvt_pk_bf16_f32 v50, v48, v49
	s_nop 0
	v_mul_f32_e32 v52, 0x3fb8aa3b, v52
	s_nop 0
	s_nop 0
	v_exp_f32_e32 v52, v52
	global_store_dword v44, v50, s[100:101]
	s_add_u32 s100, s100, 0x2c00
	s_addc_u32 s101, s101, 0
	v_fma_f32 v50, v5, v70, v17
	v_and_b32_e32 v61, 0xffff0000, v64
	v_fmac_f32_e32 v50, v9, v57
	v_fmac_f32_e32 v50, v13, v61
	v_add_f32_e32 v49, 1.0, v52
	v_mul_f32_e32 v52, 0x3d372713, v50
	v_mul_f32_e32 v52, v50, v52
	v_fma_f32 v52, v50, v52, v50
	v_mul_f32_e32 v52, 0xbfcc422a, v52
	v_rcp_f32_e32 v49, v49
	v_mul_f32_e32 v52, 0x3fb8aa3b, v52
	v_exp_f32_e32 v52, v52
	v_fma_f32 v48, v6, v72, v18
	v_lshlrev_b32_e32 v62, 16, v65
	v_fmac_f32_e32 v48, v10, v58
	v_fmac_f32_e32 v48, v14, v62
	v_mul_f32_e32 v49, v51, v49
	v_mul_f32_e32 v48, v48, v49
	v_add_f32_e32 v49, 1.0, v52
	v_rcp_f32_e32 v49, v49
	v_fma_f32 v51, v7, v69, v19
	v_and_b32_e32 v60, 0xffff0000, v65
	v_fmac_f32_e32 v51, v42, v56
	v_fmac_f32_e32 v51, v40, v60
	v_mul_f32_e32 v49, v50, v49
	v_mul_f32_e32 v49, v51, v49
	v_cvt_pk_bf16_f32 v50, v48, v49
	s_nop 0
	v_mov_b32_e32 v52, v62
	s_nop 0
	s_nop 0
	v_mov_b32_e32 v53, v60
	v_mov_b32_e32 v54, v63
	v_mov_b32_e32 v55, v61
	global_store_dword v44, v50, s[100:101]
	s_add_u32 s100, s100, 0x2c00
	s_addc_u32 s101, s101, 0
	s_mov_b64 s[6:7], -1
	s_and_b64 vcc, exec, s[0:1]
	v_mov_b64_e32 v[48:49], v[54:55]
	v_mov_b64_e32 v[50:51], v[52:53]
	s_cbranch_vccnz .LBB0_807
	s_add_i32 s6, s84, 14
	s_and_b32 s6, s6, 0x7fe
	v_mov_b32_e32 v64, v62
	v_mov_b32_e32 v65, v60
	v_mov_b32_e32 v66, v63
	v_mov_b32_e32 v67, v61
	s_cmpk_eq_i32 s6, 0x7fe
	s_mov_b64 s[6:7], -1
	v_mov_b64_e32 v[48:49], v[66:67]
	v_mov_b64_e32 v[50:51], v[64:65]
	s_cbranch_scc1 .LBB0_804
	v_mov_b32_e32 v48, v63
	v_mov_b32_e32 v49, v61
	v_mov_b32_e32 v50, v62
	v_mov_b32_e32 v51, v60
	s_mov_b64 s[6:7], 0

; __device__ __forceinline__ unsigned pk2(float lo, float hi) { unsigned r; asm("v_cvt_pk_bf16_f32 %0, %1, %2" : "=v"(r) : "v"(lo), "v"(hi)); return r; }
; __device__ __forceinline__ float gelu_t(float x) { return x * __builtin_amdgcn_rcpf(1.f + __expf(-1.5957691216057308f * (x + 0.044715f * x * x * x))); }
; __device__ __forceinline__ void act_item(int item, u16* UP, const u16* HALO, const float* sconv, const float* wconv, const float* bconv, float* out, int lane) {
;     ...
;             for (int p = 0; p < 2; ++p) { const float cgv = bg[p] + wgt[0][p] * g2[p] + wgt[1][p] * g1[p] + wgt[2][p] * g0[p];
;                 const float cvv = bv[p] + wvl[0][p] * v2[p] + wvl[1][p] * v1[p] + wvl[2][p] * v0[p]; res[p] = gelu_t(cgv) * cvv;
;                 g2[p] = g1[p]; g1[p] = g0[p]; v2[p] = v1[p]; v1[p] = v0[p]; }
;             *(unsigned*)(UP + (size_t)row * FF2 + j0) = pk2(res[0], res[1]);
;             if (!sample) { const int tq = row & 2047; if (tq >= 2046) { float* o = out + O_CONVP + ((size_t)(row >> 11) * 2 + (tq - 2046)) * FF2;
;                     *(f32x2*)(o + j0) = (f32x2){g0[0], g0[1]}; *(f32x2*)(o + FF + j0) = (f32x2){v0[0], v0[1]}; } }
.LBB0_809:
	v_lshlrev_b32_e32 v54, 16, v68
	v_and_b32_e32 v55, 0xffff0000, v68
	v_pk_fma_f32 v[58:59], v[26:27], v[58:59], v[24:25]
	v_pk_fma_f32 v[56:57], v[34:35], v[56:57], v[32:33]
	v_lshlrev_b32_e32 v65, 16, v1
	v_mov_b32_e32 v64, v54
	v_and_b32_e32 v53, 0xffff0000, v1
	v_mov_b32_e32 v52, v55
	v_pk_fma_f32 v[58:59], v[28:29], v[62:63], v[58:59]
	v_pk_fma_f32 v[56:57], v[36:37], v[60:61], v[56:57]
	v_pk_fma_f32 v[58:59], v[30:31], v[64:65], v[58:59]
	v_pk_fma_f32 v[56:57], v[38:39], v[52:53], v[56:57]
	v_mul_f32_e32 v1, 0x3d372713, v59
	v_mul_f32_e32 v52, 0x3d372713, v57
	v_mul_f32_e32 v1, v59, v1
	v_mul_f32_e32 v52, v57, v52
	v_fma_f32 v1, v59, v1, v59
	v_fma_f32 v52, v57, v52, v57
	v_mul_f32_e32 v1, 0xbfcc422a, v1
	v_mul_f32_e32 v52, 0xbfcc422a, v52
	v_mul_f32_e32 v1, 0x3fb8aa3b, v1
	v_mul_f32_e32 v52, 0x3fb8aa3b, v52
	v_exp_f32_e32 v1, v1
	v_exp_f32_e32 v52, v52
	s_nop 0
	v_add_f32_e32 v1, 1.0, v1
	v_add_f32_e32 v52, 1.0, v52
	v_rcp_f32_e32 v1, v1
	v_rcp_f32_e32 v52, v52
	s_nop 0
	v_mul_f32_e32 v1, v59, v1
	v_mul_f32_e32 v52, v57, v52
	v_mul_f32_e32 v1, v58, v1
	v_mul_f32_e32 v56, v56, v52
	v_mov_b32_e32 v52, v65
	s_and_b64 vcc, exec, s[0:1]
	v_cvt_pk_bf16_f32 v1, v1, v56
	global_store_dword v44, v1, s[100:101]
	s_add_u32 s100, s100, 0x2c00
	s_addc_u32 s101, s101, 0
	s_cbranch_vccnz .LBB0_814
	s_add_i32 s85, s82, s83
	s_add_i32 s0, s85, 15
	s_mov_b64 s[6:7], 0
	s_cmpk_gt_u32 s0, 0x7fd
	s_mov_b64 s[68:69], 0
	s_cbranch_scc0 .LBB0_815
	s_addk_i32 s85, 0xf811
	s_add_u32 s0, s62, s85
	s_addc_u32 s1, s63, 0
	s_mulk_i32 s1, 0x5800
	s_mul_hi_u32 s68, s0, 0x5800
	s_add_i32 s68, s68, s1
	s_mulk_i32 s0, 0x5800
	s_add_u32 s0, s3, s0
	s_addc_u32 s1, s21, s68
	v_lshl_add_u64 v[46:47], v[2:3], 2, s[0:1]
	s_add_u32 s0, s0, 0x2c00
	global_store_dwordx2 v[46:47], v[52:53], off
	s_addc_u32 s1, s1, 0
	s_mov_b64 s[68:69], -1
	s_branch .LBB0_815
